# P3 final epilogue rewritten by hand: per-head sums of squares loaded four rows at a time instead of row by row behind the previous stores
# baseline (speedup 1.0000x reference)
.LBB0_402:
	v_readlane_b32 s8, v244, 24
	v_readlane_b32 s9, v244, 25
	v_add_u32_e32 v216, s17, v172
	v_mul_u32_u24_e32 v217, 48, v216
	v_lshl_or_b32 v218, s56, 8, v174
	v_lshlrev_b32_e32 v218, 1, v218
	v_lshl_add_u32 v218, v216, 11, v218
	v_mov_b32_e32 v219, v217
	global_load_dwordx4 v[132:135], v219, s[10:11] offset:0
	global_load_dwordx4 v[136:139], v219, s[10:11] offset:16
	global_load_dwordx4 v[140:143], v219, s[10:11] offset:32
	global_load_dwordx4 v[144:147], v219, s[10:11] offset:768
	global_load_dwordx4 v[148:151], v219, s[10:11] offset:784
	global_load_dwordx4 v[180:183], v219, s[10:11] offset:800
	global_load_dwordx4 v[184:187], v219, s[10:11] offset:1536
	global_load_dwordx4 v[188:191], v219, s[10:11] offset:1552
	global_load_dwordx4 v[192:195], v219, s[10:11] offset:1568
	global_load_dwordx4 v[196:199], v219, s[10:11] offset:2304
	global_load_dwordx4 v[200:203], v219, s[10:11] offset:2320
	global_load_dwordx4 v[204:207], v219, s[10:11] offset:2336
	s_waitcnt vmcnt(0)
	v_add_f32_e32 v132, v132, v133
	v_add_f32_e32 v134, v134, v135
	v_add_f32_e32 v136, v136, v137
	v_add_f32_e32 v138, v138, v139
	v_add_f32_e32 v140, v140, v141
	v_add_f32_e32 v142, v142, v143
	v_add_f32_e32 v132, v132, v134
	v_add_f32_e32 v136, v136, v138
	v_add_f32_e32 v140, v140, v142
	v_add_f32_e32 v132, v132, v136
	v_add_f32_e32 v220, v132, v140
	v_add_f32_e32 v144, v144, v145
	v_add_f32_e32 v146, v146, v147
	v_add_f32_e32 v148, v148, v149
	v_add_f32_e32 v150, v150, v151
	v_add_f32_e32 v180, v180, v181
	v_add_f32_e32 v182, v182, v183
	v_add_f32_e32 v144, v144, v146
	v_add_f32_e32 v148, v148, v150
	v_add_f32_e32 v180, v180, v182
	v_add_f32_e32 v144, v144, v148
	v_add_f32_e32 v222, v144, v180
	v_add_f32_e32 v184, v184, v185
	v_add_f32_e32 v186, v186, v187
	v_add_f32_e32 v188, v188, v189
	v_add_f32_e32 v190, v190, v191
	v_add_f32_e32 v192, v192, v193
	v_add_f32_e32 v194, v194, v195
	v_add_f32_e32 v184, v184, v186
	v_add_f32_e32 v188, v188, v190
	v_add_f32_e32 v192, v192, v194
	v_add_f32_e32 v184, v184, v188
	v_add_f32_e32 v224, v184, v192
	v_add_f32_e32 v196, v196, v197
	v_add_f32_e32 v198, v198, v199
	v_add_f32_e32 v200, v200, v201
	v_add_f32_e32 v202, v202, v203
	v_add_f32_e32 v204, v204, v205
	v_add_f32_e32 v206, v206, v207
	v_add_f32_e32 v196, v196, v198
	v_add_f32_e32 v200, v200, v202
	v_add_f32_e32 v204, v204, v206
	v_add_f32_e32 v196, v196, v200
	v_add_f32_e32 v226, v196, v204
	v_add_u32_e32 v219, 0x1800, v217
	global_load_dwordx4 v[132:135], v219, s[10:11] offset:0
	global_load_dwordx4 v[136:139], v219, s[10:11] offset:16
	global_load_dwordx4 v[140:143], v219, s[10:11] offset:32
	global_load_dwordx4 v[144:147], v219, s[10:11] offset:768
	global_load_dwordx4 v[148:151], v219, s[10:11] offset:784
	global_load_dwordx4 v[180:183], v219, s[10:11] offset:800
	global_load_dwordx4 v[184:187], v219, s[10:11] offset:1536
	global_load_dwordx4 v[188:191], v219, s[10:11] offset:1552
	global_load_dwordx4 v[192:195], v219, s[10:11] offset:1568
	global_load_dwordx4 v[196:199], v219, s[10:11] offset:2304
	global_load_dwordx4 v[200:203], v219, s[10:11] offset:2320
	global_load_dwordx4 v[204:207], v219, s[10:11] offset:2336
	v_fmamk_f32 v220, v220, 0x3aaaaaab, v175
	v_sqrt_f32_e32 v228, v220
	s_nop 0
	v_add_u32_e32 v229, -1, v228
	v_add_u32_e32 v230, 1, v228
	v_fma_f32 v231, -v229, v228, v220
	v_fma_f32 v232, -v230, v228, v220
	v_cmp_ge_f32_e32 vcc, 0, v231
	s_nop 1
	v_cndmask_b32_e32 v228, v228, v229, vcc
	v_cmp_lt_f32_e32 vcc, 0, v232
	s_nop 1
	v_cndmask_b32_e32 v228, v228, v230, vcc
	v_div_scale_f32 v229, vcc, v228, v228, 1.0
	v_rcp_f32_e32 v230, v229
	v_div_scale_f32 v231, vcc, 1.0, v228, 1.0
	v_fma_f32 v232, -v229, v230, 1.0
	v_fmac_f32_e32 v230, v232, v230
	v_mul_f32_e32 v232, v231, v230
	v_fma_f32 v233, -v229, v232, v231
	v_fmac_f32_e32 v232, v233, v230
	v_fma_f32 v229, -v229, v232, v231
	s_nop 1
	v_div_fmas_f32 v229, v229, v230, v232
	v_div_fixup_f32 v220, v229, v228, 1.0
	v_fmamk_f32 v222, v222, 0x3aaaaaab, v175
	v_sqrt_f32_e32 v228, v222
	s_nop 0
	v_add_u32_e32 v229, -1, v228
	v_add_u32_e32 v230, 1, v228
	v_fma_f32 v231, -v229, v228, v222
	v_fma_f32 v232, -v230, v228, v222
	v_cmp_ge_f32_e32 vcc, 0, v231
	s_nop 1
	v_cndmask_b32_e32 v228, v228, v229, vcc
	v_cmp_lt_f32_e32 vcc, 0, v232
	s_nop 1
	v_cndmask_b32_e32 v228, v228, v230, vcc
	v_div_scale_f32 v229, vcc, v228, v228, 1.0
	v_rcp_f32_e32 v230, v229
	v_div_scale_f32 v231, vcc, 1.0, v228, 1.0
	v_fma_f32 v232, -v229, v230, 1.0
	v_fmac_f32_e32 v230, v232, v230
	v_mul_f32_e32 v232, v231, v230
	v_fma_f32 v233, -v229, v232, v231
	v_fmac_f32_e32 v232, v233, v230
	v_fma_f32 v229, -v229, v232, v231
	s_nop 1
	v_div_fmas_f32 v229, v229, v230, v232
	v_div_fixup_f32 v222, v229, v228, 1.0
	v_fmamk_f32 v224, v224, 0x3aaaaaab, v175
	v_sqrt_f32_e32 v228, v224
	s_nop 0
	v_add_u32_e32 v229, -1, v228
	v_add_u32_e32 v230, 1, v228
	v_fma_f32 v231, -v229, v228, v224
	v_fma_f32 v232, -v230, v228, v224
	v_cmp_ge_f32_e32 vcc, 0, v231
	s_nop 1
	v_cndmask_b32_e32 v228, v228, v229, vcc
	v_cmp_lt_f32_e32 vcc, 0, v232
	s_nop 1
	v_cndmask_b32_e32 v228, v228, v230, vcc
	v_div_scale_f32 v229, vcc, v228, v228, 1.0
	v_rcp_f32_e32 v230, v229
	v_div_scale_f32 v231, vcc, 1.0, v228, 1.0
	v_fma_f32 v232, -v229, v230, 1.0
	v_fmac_f32_e32 v230, v232, v230
	v_mul_f32_e32 v232, v231, v230
	v_fma_f32 v233, -v229, v232, v231
	v_fmac_f32_e32 v232, v233, v230
	v_fma_f32 v229, -v229, v232, v231
	s_nop 1
	v_div_fmas_f32 v229, v229, v230, v232
	v_div_fixup_f32 v224, v229, v228, 1.0
	v_fmamk_f32 v226, v226, 0x3aaaaaab, v175
	v_sqrt_f32_e32 v228, v226
	s_nop 0
	v_add_u32_e32 v229, -1, v228
	v_add_u32_e32 v230, 1, v228
	v_fma_f32 v231, -v229, v228, v226
	v_fma_f32 v232, -v230, v228, v226
	v_cmp_ge_f32_e32 vcc, 0, v231
	s_nop 1
	v_cndmask_b32_e32 v228, v228, v229, vcc
	v_cmp_lt_f32_e32 vcc, 0, v232
	s_nop 1
	v_cndmask_b32_e32 v228, v228, v230, vcc
	v_div_scale_f32 v229, vcc, v228, v228, 1.0
	v_rcp_f32_e32 v230, v229
	v_div_scale_f32 v231, vcc, 1.0, v228, 1.0
	v_fma_f32 v232, -v229, v230, 1.0
	v_fmac_f32_e32 v230, v232, v230
	v_mul_f32_e32 v232, v231, v230
	v_fma_f32 v233, -v229, v232, v231
	v_fmac_f32_e32 v232, v233, v230
	v_fma_f32 v229, -v229, v232, v231
	s_nop 1
	v_div_fmas_f32 v229, v229, v230, v232
	v_div_fixup_f32 v226, v229, v228, 1.0
	v_mov_b32_e32 v238, v218
	v_pk_mul_f32 v[128:129], v[128:129], v[220:221] op_sel_hi:[1,0]
	v_pk_mul_f32 v[130:131], v[130:131], v[220:221] op_sel_hi:[1,0]
	v_pk_mul_f32 v[124:125], v[124:125], v[220:221] op_sel_hi:[1,0]
	v_pk_mul_f32 v[126:127], v[126:127], v[220:221] op_sel_hi:[1,0]
	v_pk_mul_f32 v[120:121], v[120:121], v[220:221] op_sel_hi:[1,0]
	v_pk_mul_f32 v[122:123], v[122:123], v[220:221] op_sel_hi:[1,0]
	v_pk_mul_f32 v[116:117], v[116:117], v[220:221] op_sel_hi:[1,0]
	v_pk_mul_f32 v[118:119], v[118:119], v[220:221] op_sel_hi:[1,0]
	v_cvt_pk_bf16_f32 v128, v128, v129
	v_cvt_pk_bf16_f32 v129, v130, v131
	v_cvt_pk_bf16_f32 v130, v124, v125
	v_cvt_pk_bf16_f32 v131, v126, v127
	global_store_dwordx4 v238, v[128:131], s[8:9]
	v_cvt_pk_bf16_f32 v120, v120, v121
	v_cvt_pk_bf16_f32 v121, v122, v123
	v_cvt_pk_bf16_f32 v122, v116, v117
	v_cvt_pk_bf16_f32 v123, v118, v119
	global_store_dwordx4 v238, v[120:123], s[8:9] offset:256
	s_nop 1
	v_add_u32_e32 v238, 0x8000, v218
	v_pk_mul_f32 v[112:113], v[112:113], v[222:223] op_sel_hi:[1,0]
	v_pk_mul_f32 v[114:115], v[114:115], v[222:223] op_sel_hi:[1,0]
	v_pk_mul_f32 v[108:109], v[108:109], v[222:223] op_sel_hi:[1,0]
	v_pk_mul_f32 v[110:111], v[110:111], v[222:223] op_sel_hi:[1,0]
	v_pk_mul_f32 v[104:105], v[104:105], v[222:223] op_sel_hi:[1,0]
	v_pk_mul_f32 v[106:107], v[106:107], v[222:223] op_sel_hi:[1,0]
	v_pk_mul_f32 v[100:101], v[100:101], v[222:223] op_sel_hi:[1,0]
	v_pk_mul_f32 v[102:103], v[102:103], v[222:223] op_sel_hi:[1,0]
	v_cvt_pk_bf16_f32 v112, v112, v113
	v_cvt_pk_bf16_f32 v113, v114, v115
	v_cvt_pk_bf16_f32 v114, v108, v109
	v_cvt_pk_bf16_f32 v115, v110, v111
	global_store_dwordx4 v238, v[112:115], s[8:9]
	v_cvt_pk_bf16_f32 v104, v104, v105
	v_cvt_pk_bf16_f32 v105, v106, v107
	v_cvt_pk_bf16_f32 v106, v100, v101
	v_cvt_pk_bf16_f32 v107, v102, v103
	global_store_dwordx4 v238, v[104:107], s[8:9] offset:256
	s_nop 1
	v_add_u32_e32 v238, 0x10000, v218
	v_pk_mul_f32 v[96:97], v[96:97], v[224:225] op_sel_hi:[1,0]
	v_pk_mul_f32 v[98:99], v[98:99], v[224:225] op_sel_hi:[1,0]
	v_pk_mul_f32 v[92:93], v[92:93], v[224:225] op_sel_hi:[1,0]
	v_pk_mul_f32 v[94:95], v[94:95], v[224:225] op_sel_hi:[1,0]
	v_pk_mul_f32 v[88:89], v[88:89], v[224:225] op_sel_hi:[1,0]
	v_pk_mul_f32 v[90:91], v[90:91], v[224:225] op_sel_hi:[1,0]
	v_pk_mul_f32 v[84:85], v[84:85], v[224:225] op_sel_hi:[1,0]
	v_pk_mul_f32 v[86:87], v[86:87], v[224:225] op_sel_hi:[1,0]
	v_cvt_pk_bf16_f32 v96, v96, v97
	v_cvt_pk_bf16_f32 v97, v98, v99
	v_cvt_pk_bf16_f32 v98, v92, v93
	v_cvt_pk_bf16_f32 v99, v94, v95
	global_store_dwordx4 v238, v[96:99], s[8:9]
	v_cvt_pk_bf16_f32 v88, v88, v89
	v_cvt_pk_bf16_f32 v89, v90, v91
	v_cvt_pk_bf16_f32 v90, v84, v85
	v_cvt_pk_bf16_f32 v91, v86, v87
	global_store_dwordx4 v238, v[88:91], s[8:9] offset:256
	s_nop 1
	v_add_u32_e32 v238, 0x18000, v218
	v_pk_mul_f32 v[80:81], v[80:81], v[226:227] op_sel_hi:[1,0]
	v_pk_mul_f32 v[82:83], v[82:83], v[226:227] op_sel_hi:[1,0]
	v_pk_mul_f32 v[76:77], v[76:77], v[226:227] op_sel_hi:[1,0]
	v_pk_mul_f32 v[78:79], v[78:79], v[226:227] op_sel_hi:[1,0]
	v_pk_mul_f32 v[72:73], v[72:73], v[226:227] op_sel_hi:[1,0]
	v_pk_mul_f32 v[74:75], v[74:75], v[226:227] op_sel_hi:[1,0]
	v_pk_mul_f32 v[68:69], v[68:69], v[226:227] op_sel_hi:[1,0]
	v_pk_mul_f32 v[70:71], v[70:71], v[226:227] op_sel_hi:[1,0]
	v_cvt_pk_bf16_f32 v80, v80, v81
	v_cvt_pk_bf16_f32 v81, v82, v83
	v_cvt_pk_bf16_f32 v82, v76, v77
	v_cvt_pk_bf16_f32 v83, v78, v79
	global_store_dwordx4 v238, v[80:83], s[8:9]
	v_cvt_pk_bf16_f32 v72, v72, v73
	v_cvt_pk_bf16_f32 v73, v74, v75
	v_cvt_pk_bf16_f32 v74, v68, v69
	v_cvt_pk_bf16_f32 v75, v70, v71
	global_store_dwordx4 v238, v[72:75], s[8:9] offset:256
	s_waitcnt vmcnt(8)
	v_add_f32_e32 v132, v132, v133
	v_add_f32_e32 v134, v134, v135
	v_add_f32_e32 v136, v136, v137
	v_add_f32_e32 v138, v138, v139
	v_add_f32_e32 v140, v140, v141
	v_add_f32_e32 v142, v142, v143
	v_add_f32_e32 v132, v132, v134
	v_add_f32_e32 v136, v136, v138
	v_add_f32_e32 v140, v140, v142
	v_add_f32_e32 v132, v132, v136
	v_add_f32_e32 v220, v132, v140
	v_add_f32_e32 v144, v144, v145
	v_add_f32_e32 v146, v146, v147
	v_add_f32_e32 v148, v148, v149
	v_add_f32_e32 v150, v150, v151
	v_add_f32_e32 v180, v180, v181
	v_add_f32_e32 v182, v182, v183
	v_add_f32_e32 v144, v144, v146
	v_add_f32_e32 v148, v148, v150
	v_add_f32_e32 v180, v180, v182
	v_add_f32_e32 v144, v144, v148
	v_add_f32_e32 v222, v144, v180
	v_add_f32_e32 v184, v184, v185
	v_add_f32_e32 v186, v186, v187
	v_add_f32_e32 v188, v188, v189
	v_add_f32_e32 v190, v190, v191
	v_add_f32_e32 v192, v192, v193
	v_add_f32_e32 v194, v194, v195
	v_add_f32_e32 v184, v184, v186
	v_add_f32_e32 v188, v188, v190
	v_add_f32_e32 v192, v192, v194
	v_add_f32_e32 v184, v184, v188
	v_add_f32_e32 v224, v184, v192
	v_add_f32_e32 v196, v196, v197
	v_add_f32_e32 v198, v198, v199
	v_add_f32_e32 v200, v200, v201
	v_add_f32_e32 v202, v202, v203
	v_add_f32_e32 v204, v204, v205
	v_add_f32_e32 v206, v206, v207
	v_add_f32_e32 v196, v196, v198
	v_add_f32_e32 v200, v200, v202
	v_add_f32_e32 v204, v204, v206
	v_add_f32_e32 v196, v196, v200
	v_add_f32_e32 v226, v196, v204
	v_fmamk_f32 v220, v220, 0x3aaaaaab, v175
	v_sqrt_f32_e32 v228, v220
	s_nop 0
	v_add_u32_e32 v229, -1, v228
	v_add_u32_e32 v230, 1, v228
	v_fma_f32 v231, -v229, v228, v220
	v_fma_f32 v232, -v230, v228, v220
	v_cmp_ge_f32_e32 vcc, 0, v231
	s_nop 1
	v_cndmask_b32_e32 v228, v228, v229, vcc
	v_cmp_lt_f32_e32 vcc, 0, v232
	s_nop 1
	v_cndmask_b32_e32 v228, v228, v230, vcc
	v_div_scale_f32 v229, vcc, v228, v228, 1.0
	v_rcp_f32_e32 v230, v229
	v_div_scale_f32 v231, vcc, 1.0, v228, 1.0
	v_fma_f32 v232, -v229, v230, 1.0
	v_fmac_f32_e32 v230, v232, v230
	v_mul_f32_e32 v232, v231, v230
	v_fma_f32 v233, -v229, v232, v231
	v_fmac_f32_e32 v232, v233, v230
	v_fma_f32 v229, -v229, v232, v231
	s_nop 1
	v_div_fmas_f32 v229, v229, v230, v232
	v_div_fixup_f32 v220, v229, v228, 1.0
	v_fmamk_f32 v222, v222, 0x3aaaaaab, v175
	v_sqrt_f32_e32 v228, v222
	s_nop 0
	v_add_u32_e32 v229, -1, v228
	v_add_u32_e32 v230, 1, v228
	v_fma_f32 v231, -v229, v228, v222
	v_fma_f32 v232, -v230, v228, v222
	v_cmp_ge_f32_e32 vcc, 0, v231
	s_nop 1
	v_cndmask_b32_e32 v228, v228, v229, vcc
	v_cmp_lt_f32_e32 vcc, 0, v232
	s_nop 1
	v_cndmask_b32_e32 v228, v228, v230, vcc
	v_div_scale_f32 v229, vcc, v228, v228, 1.0
	v_rcp_f32_e32 v230, v229
	v_div_scale_f32 v231, vcc, 1.0, v228, 1.0
	v_fma_f32 v232, -v229, v230, 1.0
	v_fmac_f32_e32 v230, v232, v230
	v_mul_f32_e32 v232, v231, v230
	v_fma_f32 v233, -v229, v232, v231
	v_fmac_f32_e32 v232, v233, v230
	v_fma_f32 v229, -v229, v232, v231
	s_nop 1
	v_div_fmas_f32 v229, v229, v230, v232
	v_div_fixup_f32 v222, v229, v228, 1.0
	v_fmamk_f32 v224, v224, 0x3aaaaaab, v175
	v_sqrt_f32_e32 v228, v224
	s_nop 0
	v_add_u32_e32 v229, -1, v228
	v_add_u32_e32 v230, 1, v228
	v_fma_f32 v231, -v229, v228, v224
	v_fma_f32 v232, -v230, v228, v224
	v_cmp_ge_f32_e32 vcc, 0, v231
	s_nop 1
	v_cndmask_b32_e32 v228, v228, v229, vcc
	v_cmp_lt_f32_e32 vcc, 0, v232
	s_nop 1
	v_cndmask_b32_e32 v228, v228, v230, vcc
	v_div_scale_f32 v229, vcc, v228, v228, 1.0
	v_rcp_f32_e32 v230, v229
	v_div_scale_f32 v231, vcc, 1.0, v228, 1.0
	v_fma_f32 v232, -v229, v230, 1.0
	v_fmac_f32_e32 v230, v232, v230
	v_mul_f32_e32 v232, v231, v230
	v_fma_f32 v233, -v229, v232, v231
	v_fmac_f32_e32 v232, v233, v230
	v_fma_f32 v229, -v229, v232, v231
	s_nop 1
	v_div_fmas_f32 v229, v229, v230, v232
	v_div_fixup_f32 v224, v229, v228, 1.0
	v_fmamk_f32 v226, v226, 0x3aaaaaab, v175
	v_sqrt_f32_e32 v228, v226
	s_nop 0
	v_add_u32_e32 v229, -1, v228
	v_add_u32_e32 v230, 1, v228
	v_fma_f32 v231, -v229, v228, v226
	v_fma_f32 v232, -v230, v228, v226
	v_cmp_ge_f32_e32 vcc, 0, v231
	s_nop 1
	v_cndmask_b32_e32 v228, v228, v229, vcc
	v_cmp_lt_f32_e32 vcc, 0, v232
	s_nop 1
	v_cndmask_b32_e32 v228, v228, v230, vcc
	v_div_scale_f32 v229, vcc, v228, v228, 1.0
	v_rcp_f32_e32 v230, v229
	v_div_scale_f32 v231, vcc, 1.0, v228, 1.0
	v_fma_f32 v232, -v229, v230, 1.0
	v_fmac_f32_e32 v230, v232, v230
	v_mul_f32_e32 v232, v231, v230
	v_fma_f32 v233, -v229, v232, v231
	v_fmac_f32_e32 v232, v233, v230
	v_fma_f32 v229, -v229, v232, v231
	s_nop 1
	v_div_fmas_f32 v229, v229, v230, v232
	v_div_fixup_f32 v226, v229, v228, 1.0
	v_add_u32_e32 v238, 0x40000, v218
	v_pk_mul_f32 v[64:65], v[64:65], v[220:221] op_sel_hi:[1,0]
	v_pk_mul_f32 v[66:67], v[66:67], v[220:221] op_sel_hi:[1,0]
	v_pk_mul_f32 v[60:61], v[60:61], v[220:221] op_sel_hi:[1,0]
	v_pk_mul_f32 v[62:63], v[62:63], v[220:221] op_sel_hi:[1,0]
	v_pk_mul_f32 v[56:57], v[56:57], v[220:221] op_sel_hi:[1,0]
	v_pk_mul_f32 v[58:59], v[58:59], v[220:221] op_sel_hi:[1,0]
	v_pk_mul_f32 v[52:53], v[52:53], v[220:221] op_sel_hi:[1,0]
	v_pk_mul_f32 v[54:55], v[54:55], v[220:221] op_sel_hi:[1,0]
	v_cvt_pk_bf16_f32 v64, v64, v65
	v_cvt_pk_bf16_f32 v65, v66, v67
	v_cvt_pk_bf16_f32 v66, v60, v61
	v_cvt_pk_bf16_f32 v67, v62, v63
	global_store_dwordx4 v238, v[64:67], s[8:9]
	v_cvt_pk_bf16_f32 v56, v56, v57
	v_cvt_pk_bf16_f32 v57, v58, v59
	v_cvt_pk_bf16_f32 v58, v52, v53
	v_cvt_pk_bf16_f32 v59, v54, v55
	global_store_dwordx4 v238, v[56:59], s[8:9] offset:256
	s_nop 1
	v_add_u32_e32 v238, 0x48000, v218
	v_pk_mul_f32 v[48:49], v[48:49], v[222:223] op_sel_hi:[1,0]
	v_pk_mul_f32 v[50:51], v[50:51], v[222:223] op_sel_hi:[1,0]
	v_pk_mul_f32 v[44:45], v[44:45], v[222:223] op_sel_hi:[1,0]
	v_pk_mul_f32 v[46:47], v[46:47], v[222:223] op_sel_hi:[1,0]
	v_pk_mul_f32 v[40:41], v[40:41], v[222:223] op_sel_hi:[1,0]
	v_pk_mul_f32 v[42:43], v[42:43], v[222:223] op_sel_hi:[1,0]
	v_pk_mul_f32 v[36:37], v[36:37], v[222:223] op_sel_hi:[1,0]
	v_pk_mul_f32 v[38:39], v[38:39], v[222:223] op_sel_hi:[1,0]
	v_cvt_pk_bf16_f32 v48, v48, v49
	v_cvt_pk_bf16_f32 v49, v50, v51
	v_cvt_pk_bf16_f32 v50, v44, v45
	v_cvt_pk_bf16_f32 v51, v46, v47
	global_store_dwordx4 v238, v[48:51], s[8:9]
	v_cvt_pk_bf16_f32 v40, v40, v41
	v_cvt_pk_bf16_f32 v41, v42, v43
	v_cvt_pk_bf16_f32 v42, v36, v37
	v_cvt_pk_bf16_f32 v43, v38, v39
	global_store_dwordx4 v238, v[40:43], s[8:9] offset:256
	s_nop 1
	v_add_u32_e32 v238, 0x50000, v218
	v_pk_mul_f32 v[32:33], v[32:33], v[224:225] op_sel_hi:[1,0]
	v_pk_mul_f32 v[34:35], v[34:35], v[224:225] op_sel_hi:[1,0]
	v_pk_mul_f32 v[28:29], v[28:29], v[224:225] op_sel_hi:[1,0]
	v_pk_mul_f32 v[30:31], v[30:31], v[224:225] op_sel_hi:[1,0]
	v_pk_mul_f32 v[24:25], v[24:25], v[224:225] op_sel_hi:[1,0]
	v_pk_mul_f32 v[26:27], v[26:27], v[224:225] op_sel_hi:[1,0]
	v_pk_mul_f32 v[20:21], v[20:21], v[224:225] op_sel_hi:[1,0]
	v_pk_mul_f32 v[22:23], v[22:23], v[224:225] op_sel_hi:[1,0]
	v_cvt_pk_bf16_f32 v32, v32, v33
	v_cvt_pk_bf16_f32 v33, v34, v35
	v_cvt_pk_bf16_f32 v34, v28, v29
	v_cvt_pk_bf16_f32 v35, v30, v31
	global_store_dwordx4 v238, v[32:35], s[8:9]
	v_cvt_pk_bf16_f32 v24, v24, v25
	v_cvt_pk_bf16_f32 v25, v26, v27
	v_cvt_pk_bf16_f32 v26, v20, v21
	v_cvt_pk_bf16_f32 v27, v22, v23
	global_store_dwordx4 v238, v[24:27], s[8:9] offset:256
	s_nop 1
	v_add_u32_e32 v238, 0x58000, v218
	v_pk_mul_f32 v[16:17], v[16:17], v[226:227] op_sel_hi:[1,0]
	v_pk_mul_f32 v[18:19], v[18:19], v[226:227] op_sel_hi:[1,0]
	v_pk_mul_f32 v[12:13], v[12:13], v[226:227] op_sel_hi:[1,0]
	v_pk_mul_f32 v[14:15], v[14:15], v[226:227] op_sel_hi:[1,0]
	v_pk_mul_f32 v[8:9], v[8:9], v[226:227] op_sel_hi:[1,0]
	v_pk_mul_f32 v[10:11], v[10:11], v[226:227] op_sel_hi:[1,0]
	v_pk_mul_f32 v[4:5], v[4:5], v[226:227] op_sel_hi:[1,0]
	v_pk_mul_f32 v[6:7], v[6:7], v[226:227] op_sel_hi:[1,0]
	v_cvt_pk_bf16_f32 v16, v16, v17
	v_cvt_pk_bf16_f32 v17, v18, v19
	v_cvt_pk_bf16_f32 v18, v12, v13
	v_cvt_pk_bf16_f32 v19, v14, v15
	global_store_dwordx4 v238, v[16:19], s[8:9]
	v_cvt_pk_bf16_f32 v8, v8, v9
	v_cvt_pk_bf16_f32 v9, v10, v11
	v_cvt_pk_bf16_f32 v10, v4, v5
	v_cvt_pk_bf16_f32 v11, v6, v7
	global_store_dwordx4 v238, v[8:11], s[8:9] offset:256
	s_andn2_b64 vcc, exec, s[4:5]
	s_mov_b64 s[4:5], -1
	s_cbranch_vccnz .LBB0_393
	s_andn2_b64 vcc, exec, s[0:1]
	s_cbranch_vccnz .LBB0_392
	s_barrier
	s_branch .LBB0_392
